# FoX pair loop: next pair's LDS-DMA issue placed at the head of tile A's PV section (fills the MFMA-result wait), copy on the tile-skipped path
# baseline (speedup 1.0000x reference)
; #define LAS3 __attribute__((address_space(3)))
; __device__ __forceinline__ void fox_unit(int b, int hh, int qb, const bf16_t* Q, const bf16_t* __restrict__ K, const bf16_t* __restrict__ V, bf16_t* O, ...
;     ...
;         if (64 * jt <= qw0 + 31 && (excess || jp >= jp_lastw)) {
;             const LAS3 unsigned char* kp = kp0 + slot * SLOTB; const LAS3 unsigned char* fp = fp0 + slot * 1024;
;             asm volatile("" : "+v"(cinit));
;             f32x16 p0 = __builtin_amdgcn_mfma_f32_32x32x16_bf16(*(const LAS3 bf16x8*)(fp), qones, cinit, 0, 0, 0);
;             f32x16 p1 = __builtin_amdgcn_mfma_f32_32x32x16_bf16(*(const LAS3 bf16x8*)(fp + 512), qones, cinit, 0, 0, 0);
; #pragma unroll
;             for (int d0 = 0; d0 < 4; ++d0) {
;                 const bf16x8 k0 = *(const LAS3 bf16x8*)(kp + d0 * 2048), k1 = *(const LAS3 bf16x8*)(kp + d0 * 2048 + 512);
;                 p0 = __builtin_amdgcn_mfma_f32_32x32x16_bf16(k0, qr[d0], p0, 0, 0, 0);
;                 p1 = __builtin_amdgcn_mfma_f32_32x32x16_bf16(k1, qr[d0], p1, 0, 0, 0);
;             }
;             if (64 * jt + 63 > qw0) { const int kb_ = 64 * jt + 4 * hi - (qw0 + r32);
; #pragma unroll
;                 for (int r = 0; r < 16; ++r) { const int cr = (r & 3) + 8 * (r >> 2); if (kb_ + cr > 0) p0[r] = -INFINITY; if (kb_ + cr + 32 > 0) p1[r] = -INFINITY; } }
.LBB0_427:
	s_cmp_ge_i32 s3, s74
	s_cselect_b64 s[12:13], -1, 0
	s_or_b64 s[94:95], s[84:85], s[12:13]
	s_add_i32 s12, s96, s71
	s_add_i32 s7, s12, 0x1fc0
	s_cmp_le_u32 s7, s33
	s_cselect_b64 s[14:15], -1, 0
	s_and_b64 s[14:15], s[14:15], s[94:95]
	s_andn2_b64 vcc, exec, s[14:15]
	s_cbranch_vccnz .Lfox_skip1
	s_add_i32 s7, s6, -1
	s_and_b32 s7, s7, 3
	v_lshl_add_u32 v2, s7, 10, v166
	ds_read_b128 v[188:191], v2
	ds_read_b128 v[192:195], v2 offset:512
	s_lshl_b32 s7, s7, 13
	v_add_u32_e32 v2, s7, v137
	ds_read_b128 v[196:199], v2
	ds_read_b128 v[200:203], v2 offset:512
	ds_read_b128 v[204:207], v2 offset:2048
	ds_read_b128 v[208:211], v2 offset:2560
	ds_read_b128 v[212:215], v2 offset:4096
	ds_read_b128 v[216:219], v2 offset:4608
	ds_read_b128 v[220:223], v2 offset:6144
	ds_read_b128 v[224:227], v2 offset:6656
	s_addk_i32 s12, 0x1fff
	s_cmp_le_u32 s12, s70
	v_add_u32_e32 v186, s7, v165
	s_waitcnt lgkmcnt(9)
	v_mfma_f32_32x32x16_bf16 v[82:97], v[188:191], v[114:117], v[50:65]
	s_waitcnt lgkmcnt(8)
	v_mfma_f32_32x32x16_bf16 v[98:113], v[192:195], v[114:117], v[50:65]
	s_waitcnt lgkmcnt(7)
	v_mfma_f32_32x32x16_bf16 v[82:97], v[196:199], v[118:121], v[82:97]
	s_waitcnt lgkmcnt(6)
	v_mfma_f32_32x32x16_bf16 v[98:113], v[200:203], v[118:121], v[98:113]
	s_waitcnt lgkmcnt(5)
	v_mfma_f32_32x32x16_bf16 v[82:97], v[204:207], v[122:125], v[82:97]
	s_waitcnt lgkmcnt(4)
	v_mfma_f32_32x32x16_bf16 v[98:113], v[208:211], v[122:125], v[98:113]
	s_waitcnt lgkmcnt(3)
	v_mfma_f32_32x32x16_bf16 v[82:97], v[212:215], v[126:129], v[82:97]
	s_waitcnt lgkmcnt(2)
	v_mfma_f32_32x32x16_bf16 v[98:113], v[216:219], v[126:129], v[98:113]
	s_waitcnt lgkmcnt(1)
	v_mfma_f32_32x32x16_bf16 v[82:97], v[220:223], v[130:133], v[82:97]
	s_waitcnt lgkmcnt(0)
	v_mfma_f32_32x32x16_bf16 v[98:113], v[224:227], v[130:133], v[98:113]
	ds_read_b64_tr_b16 v[188:189], v186 offset:32768
	ds_read_b64_tr_b16 v[190:191], v186 offset:33280
	ds_read_b64_tr_b16 v[192:193], v186 offset:36864
	ds_read_b64_tr_b16 v[194:195], v186 offset:37376
	ds_read_b64_tr_b16 v[196:197], v186 offset:33792
	ds_read_b64_tr_b16 v[198:199], v186 offset:34304
	ds_read_b64_tr_b16 v[200:201], v186 offset:37888
	ds_read_b64_tr_b16 v[202:203], v186 offset:38400
	ds_read_b64_tr_b16 v[204:205], v186 offset:34816
	ds_read_b64_tr_b16 v[206:207], v186 offset:35328
	ds_read_b64_tr_b16 v[208:209], v186 offset:38912
	ds_read_b64_tr_b16 v[210:211], v186 offset:39424
	ds_read_b64_tr_b16 v[212:213], v186 offset:35840
	ds_read_b64_tr_b16 v[214:215], v186 offset:36352
	ds_read_b64_tr_b16 v[216:217], v186 offset:39936
	ds_read_b64_tr_b16 v[218:219], v186 offset:40448
	s_cbranch_scc1 .LBB0_430
	v_add_u32_e32 v2, s71, v155
	v_add_u32_e32 v2, 0xc0, v2
	s_movk_i32 s40, 0xffe6
	s_movk_i32 s68, 0xffe5
	s_movk_i32 s38, 0xffe7
	v_cmp_lt_i32_e64 s[66:67], s40, v2
	v_cmp_lt_i32_e64 s[68:69], s68, v2
	s_movk_i32 s36, 0xffe8
	v_cmp_lt_i32_e64 s[64:65], s38, v2
	s_and_b64 s[66:67], s[68:69], s[66:67]
	s_movk_i32 s34, 0xffed
	v_cmp_lt_i32_e64 s[62:63], s36, v2
	s_and_b64 s[64:65], s[66:67], s[64:65]
	s_movk_i32 s30, 0xffee
	v_cmp_lt_i32_e64 s[60:61], s34, v2
	s_and_b64 s[62:63], s[64:65], s[62:63]
	s_movk_i32 s28, 0xffef
	v_cmp_lt_i32_e64 s[58:59], s30, v2
	s_and_b64 s[60:61], s[62:63], s[60:61]
	v_cmp_lt_i32_e64 s[56:57], s28, v2
	s_and_b64 s[58:59], s[60:61], s[58:59]
	v_cmp_lt_i32_e64 s[54:55], -16, v2
	s_and_b64 s[56:57], s[58:59], s[56:57]
	v_cmp_lt_i32_e64 s[52:53], -11, v2
	s_and_b64 s[54:55], s[56:57], s[54:55]
	v_cmp_lt_i32_e64 s[50:51], -10, v2
	s_and_b64 s[52:53], s[54:55], s[52:53]
	v_cmp_lt_i32_e64 s[48:49], -9, v2
	s_and_b64 s[50:51], s[52:53], s[50:51]
	s_movk_i32 s14, 0xffe0
	v_cmp_lt_i32_e64 s[46:47], -8, v2
	s_and_b64 s[48:49], s[50:51], s[48:49]
	v_cmp_gt_i32_e64 s[12:13], 1, v2
	v_cmp_lt_i32_e32 vcc, s14, v2
	v_cmp_gt_i32_e64 s[14:15], 0, v2
	v_cmp_lt_i32_e64 s[44:45], -3, v2
	s_and_b64 s[46:47], s[48:49], s[46:47]
	s_or_b64 s[12:13], s[14:15], s[12:13]
	v_cmp_lt_i32_e64 s[42:43], -2, v2
	s_and_b64 s[44:45], s[46:47], s[44:45]
	v_cndmask_b32_e64 v4, v174, v83, s[14:15]
	v_cndmask_b32_e64 v5, v174, v82, s[12:13]
	s_and_b64 s[42:43], s[44:45], s[42:43]
	s_movk_i32 s40, 0xffc6
	v_cndmask_b32_e64 v82, v82, v5, s[42:43]
	v_cndmask_b32_e64 v84, v84, v174, s[42:43]
	v_cndmask_b32_e64 v83, v83, v4, s[42:43]
	s_movk_i32 s42, 0xffc5
	s_movk_i32 s38, 0xffc7
	v_cmp_lt_i32_e64 s[40:41], s40, v2
	v_cmp_lt_i32_e64 s[42:43], s42, v2
	s_movk_i32 s36, 0xffc8
	v_cmp_lt_i32_e64 s[38:39], s38, v2
	s_and_b64 s[40:41], s[42:43], s[40:41]
	s_movk_i32 s34, 0xffcd
	v_cmp_lt_i32_e64 s[36:37], s36, v2
	s_and_b64 s[38:39], s[40:41], s[38:39]
	s_movk_i32 s30, 0xffce
	v_cmp_lt_i32_e64 s[34:35], s34, v2
	s_and_b64 s[36:37], s[38:39], s[36:37]
	s_movk_i32 s28, 0xffcf
	v_cmp_lt_i32_e64 s[30:31], s30, v2
	s_and_b64 s[34:35], s[36:37], s[34:35]
	s_movk_i32 s26, 0xffd0
	v_cmp_lt_i32_e64 s[28:29], s28, v2
	s_and_b64 s[30:31], s[34:35], s[30:31]
	s_movk_i32 s24, 0xffd5
	v_cmp_lt_i32_e64 s[26:27], s26, v2
	s_and_b64 s[28:29], s[30:31], s[28:29]
	s_movk_i32 s22, 0xffd6
	v_cmp_lt_i32_e64 s[24:25], s24, v2
	s_and_b64 s[26:27], s[28:29], s[26:27]
	s_movk_i32 s20, 0xffd7
	v_cmp_lt_i32_e64 s[22:23], s22, v2
	s_and_b64 s[24:25], s[26:27], s[24:25]
	s_movk_i32 s18, 0xffd8
	v_cmp_lt_i32_e64 s[20:21], s20, v2
	s_and_b64 s[22:23], s[24:25], s[22:23]
	s_movk_i32 s16, 0xffdd
	v_cmp_lt_i32_e64 s[18:19], s18, v2
	s_and_b64 s[20:21], s[22:23], s[20:21]
	s_movk_i32 s14, 0xffde
	v_cmp_lt_i32_e64 s[16:17], s16, v2
	s_and_b64 s[18:19], s[20:21], s[18:19]
	s_movk_i32 s12, 0xffdf
	v_cmp_lt_i32_e64 s[14:15], s14, v2
	s_and_b64 s[16:17], s[18:19], s[16:17]
	v_cmp_lt_i32_e64 s[12:13], s12, v2
; #define LAS3 __attribute__((address_space(3)))
; __device__ __forceinline__ unsigned cvtpk(float lo, float hi) { f32x2_t v = {lo, hi}; bf16x2_t b = __builtin_convertvector(v, bf16x2_t); return __builtin_bit_cast(unsigned, b); }
; __device__ __forceinline__ s16x4 vtr(const LAS3 unsigned char* p) { return __builtin_bit_cast(s16x4, __builtin_amdgcn_ds_read_tr16_b64_v4i16((LAS3 v4i16_t*)p)); }
; __device__ __forceinline__ void fox_unit(int b, int hh, int qb, const bf16_t* Q, const bf16_t* __restrict__ K, const bf16_t* __restrict__ V, bf16_t* O, ...
;     ...
;         if (!last) { FOX_DMA(2 * jp - 1, (2 * jp - 1) & 3); FOX_DMA(2 * jp - 2, (2 * jp - 2) & 3); }
;     ...
;             for (int r = 0; r < 16; ++r) { p0[r] = __builtin_amdgcn_exp2f(p0[r]); p1[r] = __builtin_amdgcn_exp2f(p1[r]); }
;             u32x4 pw[4];
; #pragma unroll
;             for (int i = 0; i < 4; ++i) { pw[0][i] = cvtpk(p0[2 * i], p0[2 * i + 1]); pw[1][i] = cvtpk(p0[8 + 2 * i], p0[8 + 2 * i + 1]); pw[2][i] = cvtpk(p1[2 * i], p1[2 * i + 1]); pw[3][i] = cvtpk(p1[8 + 2 * i], p1[8 + 2 * i + 1]); }
;             const LAS3 unsigned char* vp = vp0 + slot * SLOTB;
; #pragma unroll
;             for (int ks = 0; ks < 4; ++ks) {
;                 const s16x4 l0 = vtr(vp + ks * 1024), h0 = vtr(vp + ks * 1024 + 512), l1 = vtr(vp + 4096 + ks * 1024), h1 = vtr(vp + 4096 + ks * 1024 + 512);
;                 const bf16x8 v0 = (bf16x8){l0[0], l0[1], l0[2], l0[3], h0[0], h0[1], h0[2], h0[3]}, v1 = (bf16x8){l1[0], l1[1], l1[2], l1[3], h1[0], h1[1], h1[2], h1[3]};
;                 const bf16x8 pf = __builtin_bit_cast(bf16x8, pw[ks]);
;                 o0 = __builtin_amdgcn_mfma_f32_32x32x16_bf16(v0, pf, o0, 0, 0, 0);
;                 o1 = __builtin_amdgcn_mfma_f32_32x32x16_bf16(v1, pf, o1, 0, 0, 0);
;                 lacc = __builtin_amdgcn_mfma_f32_32x32x16_bf16(onesA, pf, lacc, 0, 0, 0);
;             }
	s_and_b64 s[14:15], s[16:17], s[14:15]
	s_and_b64 s[12:13], s[14:15], s[12:13]
	s_and_b64 vcc, s[12:13], vcc
	v_cndmask_b32_e64 v97, v97, v174, s[68:69]
	v_cndmask_b32_e64 v96, v96, v174, s[66:67]
	v_cndmask_b32_e64 v95, v95, v174, s[64:65]
	v_cndmask_b32_e64 v94, v94, v174, s[62:63]
	v_cndmask_b32_e64 v93, v93, v174, s[60:61]
	v_cndmask_b32_e64 v92, v92, v174, s[58:59]
	v_cndmask_b32_e64 v91, v91, v174, s[56:57]
	v_cndmask_b32_e64 v90, v90, v174, s[54:55]
	v_cndmask_b32_e64 v89, v89, v174, s[52:53]
	v_cndmask_b32_e64 v88, v88, v174, s[50:51]
	v_cndmask_b32_e64 v87, v87, v174, s[48:49]
	v_cndmask_b32_e64 v86, v86, v174, s[46:47]
	v_cndmask_b32_e64 v85, v85, v174, s[44:45]
	v_cndmask_b32_e64 v113, v113, v174, s[42:43]
	v_cndmask_b32_e64 v112, v112, v174, s[40:41]
	v_cndmask_b32_e64 v111, v111, v174, s[38:39]
	v_cndmask_b32_e64 v110, v110, v174, s[36:37]
	v_cndmask_b32_e64 v109, v109, v174, s[34:35]
	v_cndmask_b32_e64 v108, v108, v174, s[30:31]
	v_cndmask_b32_e64 v107, v107, v174, s[28:29]
	v_cndmask_b32_e64 v106, v106, v174, s[26:27]
	v_cndmask_b32_e64 v105, v105, v174, s[24:25]
	v_cndmask_b32_e64 v104, v104, v174, s[22:23]
	v_cndmask_b32_e64 v103, v103, v174, s[20:21]
	v_cndmask_b32_e64 v102, v102, v174, s[18:19]
	v_cndmask_b32_e64 v101, v101, v174, s[16:17]
	v_cndmask_b32_e64 v100, v100, v174, s[14:15]
	v_cndmask_b32_e64 v99, v99, v174, s[12:13]
	v_cndmask_b32_e32 v98, v98, v174, vcc
.LBB0_430:
	s_and_b64 vcc, exec, s[86:87]
	s_cbranch_vccz .Lfox_dma_a_none
	s_add_i32 s12, s6, 1
	s_ashr_i32 s13, s12, 31
	s_and_b32 s7, s12, 3
	s_lshl_b64 s[14:15], s[12:13], 17
	s_lshl_b32 s16, s7, 13
	v_lshl_add_u64 v[4:5], v[156:157], 0, s[14:15]
	s_add_i32 s17, s16, s93
	s_mov_b32 s18, m0
	s_mov_b32 m0, s17
	s_nop 0
	global_load_lds_dwordx4 v[4:5], off
	s_mov_b32 m0, s18
	v_lshl_add_u64 v[4:5], v[158:159], 0, s[14:15]
	s_add_i32 s14, s16, s5
	s_mov_b32 s15, m0
	s_mov_b32 m0, s14
	s_nop 0
	global_load_lds_dwordx4 v[4:5], off
	s_mov_b32 m0, s15
	s_and_b64 vcc, exec, s[0:1]
	s_cbranch_vccnz .Lfox_dma_a_f
	s_lshl_b32 s7, s7, 10
	s_lshl_b64 s[12:13], s[12:13], 10
	s_add_i32 s7, s7, 0
	v_lshl_add_u64 v[4:5], v[160:161], 0, s[12:13]
	s_add_i32 s7, s7, 0x10000
	s_mov_b32 s12, m0
	s_mov_b32 m0, s7
	s_nop 0
	global_load_lds_dwordx4 v[4:5], off
	s_mov_b32 m0, s12
.Lfox_dma_a_f:
	s_ashr_i32 s7, s6, 31
	s_and_b32 s12, s6, 2
	s_lshl_b64 s[14:15], s[6:7], 17
	s_lshl_b32 s13, s12, 13
	v_lshl_add_u64 v[4:5], v[156:157], 0, s[14:15]
	s_add_i32 s16, s13, s93
	s_mov_b32 s17, m0
	s_mov_b32 m0, s16
	s_nop 0
	global_load_lds_dwordx4 v[4:5], off
	s_mov_b32 m0, s17
	v_lshl_add_u64 v[4:5], v[158:159], 0, s[14:15]
	s_add_i32 s13, s13, s5
	s_mov_b32 s14, m0
	s_mov_b32 m0, s13
	s_nop 0
	global_load_lds_dwordx4 v[4:5], off
	s_mov_b32 m0, s14
	s_and_b64 vcc, exec, s[0:1]
	s_cbranch_vccnz .Lfox_dma_a_done
	s_lshl_b64 s[14:15], s[6:7], 10
	s_lshl_b32 s7, s12, 10
	s_add_i32 s7, s7, 0
	v_lshl_add_u64 v[4:5], v[160:161], 0, s[14:15]
	s_add_i32 s7, s7, 0x10000
	s_mov_b32 s12, m0
	s_mov_b32 m0, s7
	s_nop 0
	global_load_lds_dwordx4 v[4:5], off
	s_mov_b32 m0, s12
.Lfox_dma_a_done:
	s_branch .Lfox_pv1
.Lfox_dma_a_none:
	s_nop 7
.Lfox_pv1:
	v_exp_f32_e32 v82, v82
	v_exp_f32_e32 v83, v83
	v_exp_f32_e32 v84, v84
	v_exp_f32_e32 v85, v85
	v_exp_f32_e32 v86, v86
	v_exp_f32_e32 v87, v87
	v_exp_f32_e32 v88, v88
	v_exp_f32_e32 v89, v89
	v_cvt_pk_bf16_f32 v228, v82, v83
	v_cvt_pk_bf16_f32 v229, v84, v85
	v_cvt_pk_bf16_f32 v230, v86, v87
	v_cvt_pk_bf16_f32 v231, v88, v89
	s_waitcnt lgkmcnt(0)
	s_nop 0
	v_mfma_f32_32x32x16_bf16 v[34:49], v[188:191], v[228:231], v[34:49]
	v_exp_f32_e32 v90, v90
	v_exp_f32_e32 v91, v91
	v_exp_f32_e32 v92, v92
	v_mfma_f32_32x32x16_bf16 v[18:33], v[192:195], v[228:231], v[18:33]
	v_exp_f32_e32 v93, v93
	v_exp_f32_e32 v94, v94
	v_exp_f32_e32 v95, v95
	v_exp_f32_e32 v96, v96
	v_exp_f32_e32 v97, v97
	v_add_f32_e32 v175, v175, v82
	v_add_f32_e32 v176, v176, v83
	v_add_f32_e32 v175, v175, v84
	v_add_f32_e32 v176, v176, v85
	v_cvt_pk_bf16_f32 v232, v90, v91
	v_cvt_pk_bf16_f32 v233, v92, v93
	v_cvt_pk_bf16_f32 v234, v94, v95
	v_cvt_pk_bf16_f32 v235, v96, v97
	v_add_f32_e32 v175, v175, v86
	v_add_f32_e32 v176, v176, v87
	v_mfma_f32_32x32x16_bf16 v[34:49], v[196:199], v[232:235], v[34:49]
	v_exp_f32_e32 v98, v98
	v_exp_f32_e32 v99, v99
	v_exp_f32_e32 v100, v100
	v_mfma_f32_32x32x16_bf16 v[18:33], v[200:203], v[232:235], v[18:33]
	v_exp_f32_e32 v101, v101
	v_exp_f32_e32 v102, v102
	v_exp_f32_e32 v103, v103
	v_exp_f32_e32 v104, v104
	v_exp_f32_e32 v105, v105
	v_add_f32_e32 v175, v175, v88
	v_add_f32_e32 v176, v176, v89
	v_add_f32_e32 v175, v175, v90
	v_add_f32_e32 v176, v176, v91
	v_cvt_pk_bf16_f32 v236, v98, v99
	v_cvt_pk_bf16_f32 v237, v100, v101
	v_cvt_pk_bf16_f32 v238, v102, v103
	v_cvt_pk_bf16_f32 v239, v104, v105
	v_add_f32_e32 v175, v175, v92
	v_add_f32_e32 v176, v176, v93
	v_mfma_f32_32x32x16_bf16 v[34:49], v[204:207], v[236:239], v[34:49]
	v_exp_f32_e32 v106, v106
	v_exp_f32_e32 v107, v107
	v_exp_f32_e32 v108, v108
	v_mfma_f32_32x32x16_bf16 v[18:33], v[208:211], v[236:239], v[18:33]
	v_exp_f32_e32 v109, v109
	v_exp_f32_e32 v110, v110
	v_exp_f32_e32 v111, v111
	v_exp_f32_e32 v112, v112
	v_exp_f32_e32 v113, v113
	v_add_f32_e32 v175, v175, v94
	v_add_f32_e32 v176, v176, v95
	v_add_f32_e32 v175, v175, v96
	v_add_f32_e32 v176, v176, v97
	v_cvt_pk_bf16_f32 v240, v106, v107
	v_cvt_pk_bf16_f32 v241, v108, v109
	v_cvt_pk_bf16_f32 v242, v110, v111
	v_cvt_pk_bf16_f32 v243, v112, v113
	v_add_f32_e32 v175, v175, v98
	v_add_f32_e32 v176, v176, v99
	v_mfma_f32_32x32x16_bf16 v[34:49], v[212:215], v[240:243], v[34:49]
	v_add_f32_e32 v175, v175, v100
	v_add_f32_e32 v176, v176, v101
	v_add_f32_e32 v175, v175, v102
	v_add_f32_e32 v176, v176, v103
	v_add_f32_e32 v175, v175, v104
	v_add_f32_e32 v176, v176, v105
	v_mfma_f32_32x32x16_bf16 v[18:33], v[216:219], v[240:243], v[18:33]
	v_add_f32_e32 v175, v175, v106
	v_add_f32_e32 v176, v176, v107
	v_add_f32_e32 v175, v175, v108
	v_add_f32_e32 v176, v176, v109
	v_add_f32_e32 v175, v175, v110
	v_add_f32_e32 v176, v176, v111
	v_add_f32_e32 v175, v175, v112
	v_add_f32_e32 v176, v176, v113

; __device__ __forceinline__ void fox_unit(int b, int hh, int qb, const bf16_t* Q, const bf16_t* __restrict__ K, const bf16_t* __restrict__ V, bf16_t* O, ...
;     ...
;         if (!last) { FOX_DMA(2 * jp - 1, (2 * jp - 1) & 3); FOX_DMA(2 * jp - 2, (2 * jp - 2) & 3); }
;     ...
;         if (last) break;
;     }
;     { const float inv = 1.0f / lacc[0];
; #pragma unroll
;         for (int r = 0; r < 16; ++r) { o0[r] *= inv; o1[r] *= inv; } }
;     float sq = 0.f;
; #pragma unroll
;     for (int r = 0; r < 16; ++r) sq += o0[r] * o0[r] + o1[r] * o1[r];
;     sq += other_half(sq);
;     if (hi == 0) SS[(size_t)(rowbase + qw0 + r32) * 16 + hh] = sq;
.LBB0_435:
	s_cmp_lg_u32 s3, 0
	s_cselect_b64 s[12:13], -1, 0
	s_and_b64 s[12:13], s[12:13], s[86:87]
	s_addk_i32 s71, 0xff80
	s_add_i32 s6, s6, -2
	s_and_b64 vcc, exec, s[12:13]
	s_cbranch_vccz .LBB0_437
	s_mov_b32 s3, s97
	s_branch .LBB0_420
.Lfox_skip1:
	s_and_b64 vcc, exec, s[86:87]
	s_cbranch_vccz .LBB0_431
	s_add_i32 s12, s6, 1
	s_ashr_i32 s13, s12, 31
	s_and_b32 s7, s12, 3
	s_lshl_b64 s[14:15], s[12:13], 17
	s_lshl_b32 s16, s7, 13
	v_lshl_add_u64 v[4:5], v[156:157], 0, s[14:15]
	s_add_i32 s17, s16, s93
	s_mov_b32 s18, m0
	s_mov_b32 m0, s17
	s_nop 0
	global_load_lds_dwordx4 v[4:5], off
	s_mov_b32 m0, s18
	v_lshl_add_u64 v[4:5], v[158:159], 0, s[14:15]
	s_add_i32 s14, s16, s5
	s_mov_b32 s15, m0
	s_mov_b32 m0, s14
	s_nop 0
	global_load_lds_dwordx4 v[4:5], off
	s_mov_b32 m0, s15
	s_and_b64 vcc, exec, s[0:1]
	s_cbranch_vccnz .Lfox_dma_b_f
	s_lshl_b32 s7, s7, 10
	s_lshl_b64 s[12:13], s[12:13], 10
	s_add_i32 s7, s7, 0
	v_lshl_add_u64 v[4:5], v[160:161], 0, s[12:13]
	s_add_i32 s7, s7, 0x10000
	s_mov_b32 s12, m0
	s_mov_b32 m0, s7
	s_nop 0
	global_load_lds_dwordx4 v[4:5], off
	s_mov_b32 m0, s12
.Lfox_dma_b_f:
	s_ashr_i32 s7, s6, 31
	s_and_b32 s12, s6, 2
	s_lshl_b64 s[14:15], s[6:7], 17
	s_lshl_b32 s13, s12, 13
	v_lshl_add_u64 v[4:5], v[156:157], 0, s[14:15]
	s_add_i32 s16, s13, s93
	s_mov_b32 s17, m0
	s_mov_b32 m0, s16
	s_nop 0
	global_load_lds_dwordx4 v[4:5], off
	s_mov_b32 m0, s17
	v_lshl_add_u64 v[4:5], v[158:159], 0, s[14:15]
	s_add_i32 s13, s13, s5
	s_mov_b32 s14, m0
	s_mov_b32 m0, s13
	s_nop 0
	global_load_lds_dwordx4 v[4:5], off
	s_mov_b32 m0, s14
	s_and_b64 vcc, exec, s[0:1]
	s_cbranch_vccnz .Lfox_dma_b_done
	s_lshl_b64 s[14:15], s[6:7], 10
	s_lshl_b32 s7, s12, 10
	s_add_i32 s7, s7, 0
	v_lshl_add_u64 v[4:5], v[160:161], 0, s[14:15]
	s_add_i32 s7, s7, 0x10000
	s_mov_b32 s12, m0
	s_mov_b32 m0, s7
	s_nop 0
	global_load_lds_dwordx4 v[4:5], off
	s_mov_b32 m0, s12
.Lfox_dma_b_done:
	s_branch .LBB0_431
.LBB0_437:
	v_add_f32_e32 v66, v175, v176
	v_mov_b32_e32 v175, v66
	v_mov_b32_e32 v176, v66
	s_nop 1
	v_permlane32_swap_b32_e32 v175, v176
	v_add_f32_e32 v66, v175, v176
	s_nop 4
	v_div_scale_f32 v2, s[0:1], v66, v66, 1.0
	v_rcp_f32_e32 v4, v2
	v_div_scale_f32 v5, vcc, 1.0, v66, 1.0
	v_fma_f32 v6, -v2, v4, 1.0
	v_fmac_f32_e32 v4, v6, v4
	v_mul_f32_e32 v6, v5, v4
	v_fma_f32 v7, -v2, v6, v5
	v_fmac_f32_e32 v6, v7, v4
	v_fma_f32 v2, -v2, v6, v5
	v_div_fmas_f32 v2, v2, v4, v6
	v_div_fixup_f32 v2, v2, v66, 1.0
	v_pk_mul_f32 v[6:7], v[2:3], v[34:35] op_sel_hi:[0,1]
	v_pk_mul_f32 v[4:5], v[2:3], v[18:19] op_sel_hi:[0,1]
	v_pk_mul_f32 v[14:15], v[2:3], v[36:37] op_sel_hi:[0,1]
	v_pk_mul_f32 v[10:11], v[2:3], v[20:21] op_sel_hi:[0,1]
	v_pk_mul_f32 v[20:21], v[2:3], v[24:25] op_sel_hi:[0,1]
	v_pk_mul_f32 v[24:25], v[2:3], v[30:31] op_sel_hi:[0,1]
	v_pk_mul_f32 v[30:31], v[2:3], v[32:33] op_sel_hi:[0,1]
	v_pk_mul_f32 v[32:33], v[6:7], v[6:7]
	v_pk_mul_f32 v[12:13], v[2:3], v[38:39] op_sel_hi:[0,1]
	v_pk_fma_f32 v[32:33], v[4:5], v[4:5], v[32:33]
	v_pk_mul_f32 v[38:39], v[14:15], v[14:15]
	v_pk_mul_f32 v[8:9], v[2:3], v[22:23] op_sel_hi:[0,1]
	v_pk_mul_f32 v[22:23], v[2:3], v[40:41] op_sel_hi:[0,1]
	v_pk_mul_f32 v[18:19], v[2:3], v[42:43] op_sel_hi:[0,1]
	v_pk_mul_f32 v[16:17], v[2:3], v[26:27] op_sel_hi:[0,1]
	v_pk_mul_f32 v[34:35], v[2:3], v[44:45] op_sel_hi:[0,1]
	v_pk_mul_f32 v[26:27], v[2:3], v[28:29] op_sel_hi:[0,1]
	v_pk_mul_f32 v[28:29], v[2:3], v[46:47] op_sel_hi:[0,1]
	v_pk_mul_f32 v[36:37], v[2:3], v[48:49] op_sel_hi:[0,1]
	v_pk_fma_f32 v[38:39], v[10:11], v[10:11], v[38:39]
	v_add_f32_e32 v2, v32, v33
	v_pk_mul_f32 v[40:41], v[12:13], v[12:13]
	v_add_f32_e32 v2, v38, v2
	v_pk_fma_f32 v[40:41], v[8:9], v[8:9], v[40:41]
	v_add_f32_e32 v2, v39, v2
	v_pk_mul_f32 v[42:43], v[22:23], v[22:23]
	v_add_f32_e32 v2, v40, v2
	v_pk_fma_f32 v[42:43], v[20:21], v[20:21], v[42:43]
	v_add_f32_e32 v2, v41, v2
	v_pk_mul_f32 v[44:45], v[18:19], v[18:19]
	v_add_f32_e32 v2, v42, v2
	v_pk_fma_f32 v[44:45], v[16:17], v[16:17], v[44:45]
	v_add_f32_e32 v2, v43, v2
	v_pk_mul_f32 v[46:47], v[34:35], v[34:35]
	v_add_f32_e32 v2, v44, v2
	v_pk_fma_f32 v[46:47], v[26:27], v[26:27], v[46:47]
	v_add_f32_e32 v2, v45, v2
	v_pk_mul_f32 v[48:49], v[28:29], v[28:29]
	v_add_f32_e32 v2, v46, v2
	v_pk_fma_f32 v[48:49], v[24:25], v[24:25], v[48:49]
	v_add_f32_e32 v2, v47, v2
	v_pk_mul_f32 v[50:51], v[36:37], v[36:37]
	v_add_f32_e32 v2, v48, v2
	v_pk_fma_f32 v[50:51], v[30:31], v[30:31], v[50:51]
	v_add_f32_e32 v2, v49, v2
	v_add_f32_e32 v2, v50, v2
	v_add_f32_e32 v32, v51, v2
	v_mov_b32_e32 v33, v32
	v_mov_b32_e32 v38, v32
	s_nop 1
	v_permlane32_swap_b32_e32 v33, v38
	s_and_saveexec_b64 s[0:1], s[8:9]
	s_cbranch_execz .LBB0_356
	v_or_b32_e32 v2, s80, v182
	v_readlane_b32 s2, v249, 41
	v_lshlrev_b64 v[40:41], 6, v[2:3]
	v_readlane_b32 s3, v249, 42
	v_cmp_eq_u32_e32 vcc, v33, v32
	s_nop 0
	v_lshl_add_u64 v[40:41], s[2:3], 0, v[40:41]
	v_readlane_b32 s2, v249, 60
	s_lshl_b32 s80, s2, 2
	v_cndmask_b32_e32 v2, v33, v38, vcc
	v_lshl_add_u64 v[40:41], v[40:41], 0, s[80:81]
	v_add_f32_e32 v2, v32, v2
	global_store_dword v[40:41], v2, off
	s_branch .LBB0_356
